# NA blocks: the four guarded QK fragment-read pairs issued unconditionally up front into spare quads, each guarded body waits only for its own pair
# speedup vs baseline: 1.0100x; 1.0029x over previous
.LBB0_1343:
	ds_read_b128 v[132:135], v118
	ds_read_b128 v[136:139], v118 offset:64
	ds_read_b128 v[140:143], v96 offset:2304
	ds_read_b128 v[144:147], v96 offset:2368
	ds_read_b128 v[148:151], v96 offset:4608
	ds_read_b128 v[152:155], v96 offset:4672
	ds_read_b128 v[156:159], v96 offset:6912
	ds_read_b128 v[160:163], v96 offset:6976
	s_cmp_lt_u32 s68, 8
	s_cselect_b64 s[18:19], -1, 0
	s_and_b64 s[20:21], s[18:19], exec
	s_cselect_b32 s25, s65, 0
	s_cselect_b32 s24, s33, 3
	s_cmp_lg_u32 s25, 0
	s_cselect_b64 s[20:21], -1, 0
	s_cmp_lt_i32 s24, 0
	s_cselect_b64 s[96:97], -1, 0
	s_or_b64 s[22:23], s[20:21], s[96:97]
	v_mov_b32_e32 v76, 0
	s_and_b64 vcc, exec, s[22:23]
	v_mov_b32_e32 v68, 0
	v_mov_b32_e32 v69, v76
	v_mov_b32_e32 v70, v76
	v_mov_b32_e32 v71, v76
	s_cbranch_vccnz .LBB0_1345
	s_waitcnt lgkmcnt(6)
	v_mfma_f32_16x16x32_bf16 v[60:63], v[132:135], v[0:3], 0
	s_nop 0
	v_mfma_f32_16x16x32_bf16 v[68:71], v[136:139], v[8:11], v[60:63]
.LBB0_1345:
	s_cmp_gt_u32 s25, 1
	s_cselect_b64 s[60:61], -1, 0
	s_cmp_lt_i32 s24, 1
	s_cselect_b64 s[20:21], -1, 0
	s_or_b64 s[20:21], s[60:61], s[20:21]
	s_and_b64 vcc, exec, s[20:21]
	v_mov_b32_e32 v77, 0
	v_mov_b32_e32 v78, 0
	v_mov_b32_e32 v79, 0
	s_cbranch_vccnz .LBB0_1347
	s_waitcnt lgkmcnt(4)
	v_mfma_f32_16x16x32_bf16 v[60:63], v[140:143], v[0:3], 0
	s_nop 0
	v_mfma_f32_16x16x32_bf16 v[76:79], v[144:147], v[8:11], v[60:63]
.LBB0_1347:
	s_cmp_gt_u32 s25, 2
	s_cselect_b64 s[26:27], -1, 0
	s_cmp_lt_i32 s24, 2
	s_cselect_b64 s[92:93], -1, 0
	s_or_b64 s[26:27], s[26:27], s[92:93]
	s_nop 0
	v_mov_b32_e32 v60, 0
	s_and_b64 vcc, exec, s[26:27]
	v_mov_b32_e32 v72, 0
	v_mov_b32_e32 v73, 0
	v_mov_b32_e32 v74, 0
	v_mov_b32_e32 v75, 0
	s_cbranch_vccnz .LBB0_1349
	s_waitcnt lgkmcnt(2)
	v_mfma_f32_16x16x32_bf16 v[62:65], v[148:151], v[0:3], 0
	s_nop 0
	v_mfma_f32_16x16x32_bf16 v[72:75], v[152:155], v[8:11], v[62:65]
.LBB0_1349:
	s_cmp_gt_u32 s25, 3
	s_cselect_b64 s[58:59], -1, 0
	s_cmp_lt_i32 s24, 3
	s_cselect_b64 s[24:25], -1, 0
	s_or_b64 s[62:63], s[58:59], s[24:25]
	s_and_b64 vcc, exec, s[62:63]
	v_mov_b32_e32 v61, 0
	v_mov_b32_e32 v62, 0
	v_mov_b32_e32 v63, 0
	s_cbranch_vccnz .LBB0_1351
	s_waitcnt lgkmcnt(0)
	v_mfma_f32_16x16x32_bf16 v[60:63], v[156:159], v[0:3], 0
	s_nop 0
	v_mfma_f32_16x16x32_bf16 v[60:63], v[160:163], v[8:11], v[60:63]
.LBB0_1351:
	s_waitcnt lgkmcnt(0)
	v_cndmask_b32_e64 v4, 0, 1, s[18:19]
	s_andn2_b64 vcc, exec, s[18:19]
	s_xor_b64 s[18:19], s[22:23], -1
	s_xor_b64 s[24:25], s[20:21], -1
	v_cmp_ne_u32_e64 s[20:21], 1, v4
	v_cndmask_b32_e64 v4, 0, 1, s[18:19]
	s_xor_b64 s[26:27], s[26:27], -1
	s_xor_b64 s[62:63], s[62:63], -1
	v_cmp_ne_u32_e64 s[18:19], 1, v4
	s_cbranch_vccnz .LBB0_1393
	v_mov_b32_e32 v67, 0xf149f2ca
	s_and_b64 vcc, exec, s[18:19]
	v_mov_b32_e32 v66, 0xf149f2ca
	v_mov_b32_e32 v65, 0xf149f2ca
	v_mov_b32_e32 v64, 0xf149f2ca
	s_cbranch_vccnz .LBB0_1362
	v_mov_b32_e32 v65, 0xf149f2ca
	v_mov_b32_e32 v64, 0xf149f2ca
	v_mov_b32_e32 v67, 0xf149f2ca
	v_mov_b32_e32 v66, 0xf149f2ca
	v_add_u32_e32 v132, s72, v113
	ds_read_b32 v132, v132 offset:37732
	v_add_u32_e32 v133, s72, v112
	ds_read_b32 v133, v133 offset:37732
	v_add_u32_e32 v134, s72, v111
	ds_read_b32 v134, v134 offset:37732
	v_add_u32_e32 v135, s72, v110
	ds_read_b32 v135, v135 offset:37732
	s_waitcnt lgkmcnt(0)
	v_add_f32_e32 v132, v68, v132
	v_cndmask_b32_e64 v64, v64, v132, s[0:1]
	v_add_f32_e32 v133, v69, v133
	v_cndmask_b32_e64 v65, v65, v133, s[4:5]
	v_add_f32_e32 v134, v70, v134
	v_cndmask_b32_e64 v66, v66, v134, s[6:7]
	v_add_f32_e32 v135, v71, v135
	v_cndmask_b32_e64 v67, v67, v135, s[8:9]

.LBB0_3331:
	ds_read_b128 v[132:135], v118
	ds_read_b128 v[136:139], v118 offset:64
	ds_read_b128 v[140:143], v96 offset:2304
	ds_read_b128 v[144:147], v96 offset:2368
	ds_read_b128 v[148:151], v96 offset:4608
	ds_read_b128 v[152:155], v96 offset:4672
	ds_read_b128 v[156:159], v96 offset:6912
	ds_read_b128 v[160:163], v96 offset:6976
	s_cmp_lt_u32 s68, 8
	s_cselect_b64 s[18:19], -1, 0
	s_and_b64 s[20:21], s[18:19], exec
	s_cselect_b32 s25, s57, 0
	s_cselect_b32 s24, s88, 3
	s_cmp_lg_u32 s25, 0
	s_cselect_b64 s[20:21], -1, 0
	s_cmp_lt_i32 s24, 0
	s_cselect_b64 s[96:97], -1, 0
	s_or_b64 s[22:23], s[20:21], s[96:97]
	v_mov_b32_e32 v76, 0
	s_and_b64 vcc, exec, s[22:23]
	v_mov_b32_e32 v68, 0
	v_mov_b32_e32 v69, v76
	v_mov_b32_e32 v70, v76
	v_mov_b32_e32 v71, v76
	s_cbranch_vccnz .LBB0_3333
	s_waitcnt lgkmcnt(6)
	v_mfma_f32_16x16x32_bf16 v[60:63], v[132:135], v[0:3], 0
	s_nop 0
	v_mfma_f32_16x16x32_bf16 v[68:71], v[136:139], v[8:11], v[60:63]

.LBB0_3335:
	s_cmp_gt_u32 s25, 2
	s_cselect_b64 s[26:27], -1, 0
	s_cmp_lt_i32 s24, 2
	s_cselect_b64 s[54:55], -1, 0
	s_or_b64 s[26:27], s[26:27], s[54:55]
	s_nop 0
	v_mov_b32_e32 v60, 0
	s_and_b64 vcc, exec, s[26:27]
	v_mov_b32_e32 v72, 0
	v_mov_b32_e32 v73, 0
	v_mov_b32_e32 v74, 0
	v_mov_b32_e32 v75, 0
	s_cbranch_vccnz .LBB0_3337
	s_waitcnt lgkmcnt(2)
	v_mfma_f32_16x16x32_bf16 v[62:65], v[148:151], v[0:3], 0
	s_nop 0
	v_mfma_f32_16x16x32_bf16 v[72:75], v[152:155], v[8:11], v[62:65]
